# phase A row loop: both rows' x/out loads issued together (row0 out dests renamed to v100-107), counted waits 7..0
# speedup vs baseline: 1.0045x; 1.0045x over previous
; __device__ __forceinline__ float bf2f(unsigned b) { return __uint_as_float(b << 16); }
; __device__ __forceinline__ void phaseA(const Params& p, int l, unsigned char* lds, int wid0) {
;     ...
;     for (int r0 = gw; r0 < nrows; r0 += 2 * NGW) {
;         const int r1 = r0 + NGW; const bool two = r1 < nrows;
;         f32x4 v[2][4], o[2][4]; const float* xs[2]; float* xd[2]; int cond[2]; int rr[2] = {r0, two ? r1 : r0};
; #pragma unroll
;         for (int k = 0; k < 2; ++k) { const int r = rr[k]; const bool isctx = r >= MLAT; cond[k] = isctx ? 2 : (r >> 13);
;             if (!isctx) { xs[k] = (l <= 1 ? p.in[I_X] : p.out) + (size_t)r * 1024; xd[k] = p.out + (size_t)r * 1024; }
;             else { xs[k] = (l <= 1 ? p.in[I_CTX] : xc) + (size_t)(r - MLAT) * 1024; xd[k] = xc + (size_t)(r - MLAT) * 1024; }
; #pragma unroll
;             for (int j = 0; j < 4; ++j) v[k][j] = *(const f32x4*)(xs[k] + 4 * lane + 256 * j);
;             if (l > 0) {
; #pragma unroll
;                 for (int j = 0; j < 4; ++j) { const u32x2 w = *(const u32x2*)(outb + (size_t)r * 1024 + 4 * lane + 256 * j); o[k][j] = (f32x4){bf2f(w.x & 0xffffu), bf2f(w.x >> 16), bf2f(w.y & 0xffffu), bf2f(w.y >> 16)}; } } }
.LBB0_562:
	s_add_i32 s46, s75, 0xffffc000
	v_readlane_b32 s4, v253, 55
	v_readlane_b32 s5, v253, 56
	s_add_u32 s47, s4, s42
	s_addc_u32 s48, s5, s43
	s_cmpk_gt_i32 s75, 0x3fff
	s_cselect_b64 s[62:63], -1, 0
	s_and_b64 s[44:45], s[62:63], exec
	s_cselect_b32 s65, 0, s48
	s_cselect_b32 s64, s46, s47
	s_cselect_b32 s46, s73, s61
	s_cselect_b32 s47, s74, s72
	s_lshl_b64 s[44:45], s[64:65], 12
	s_add_u32 s44, s47, s44
	s_addc_u32 s45, s46, s45
	s_waitcnt vmcnt(4)
	v_lshl_add_u64 v[0:1], v[32:33], 2, s[44:45]
	global_load_dwordx4 v[20:23], v[0:1], off
	global_load_dwordx4 v[8:11], v[0:1], off offset:1024
	s_waitcnt lgkmcnt(0)
	global_load_dwordx4 v[4:7], v[0:1], off offset:2048
	s_nop 0
	global_load_dwordx4 v[0:3], v[0:1], off offset:3072
	s_add_i32 s44, s26, s75
	s_cmp_lt_i32 s44, s27
	s_cselect_b64 s[46:47], -1, 0
	s_and_b64 s[48:49], s[46:47], exec
	s_cselect_b32 s48, s44, s75
	s_cmpk_gt_i32 s48, 0x3fff
	s_cselect_b64 s[54:55], -1, 0
	s_add_i32 s45, s48, 0xffffc000
	s_ashr_i32 s49, s48, 31
	s_and_b64 s[58:59], s[54:55], exec
	s_cselect_b32 s59, 0, s49
	s_cselect_b32 s58, s45, s48
	s_cselect_b32 s45, s73, s61
	s_cselect_b32 s82, s74, s72
	s_lshl_b64 s[76:77], s[58:59], 12
	s_add_u32 s76, s82, s76
	s_addc_u32 s77, s45, s77
	s_waitcnt vmcnt(4)
	v_lshl_add_u64 v[12:13], v[32:33], 2, s[76:77]
	global_load_dwordx4 v[28:31], v[12:13], off
	global_load_dwordx4 v[24:27], v[12:13], off offset:1024
	global_load_dwordx4 v[16:19], v[12:13], off offset:2048
	s_nop 0
	global_load_dwordx4 v[12:15], v[12:13], off offset:3072
	v_readlane_b32 s4, v251, 25
	s_and_b64 vcc, exec, s[34:35]
	s_cbranch_vccz .LBB0_566
	global_load_dwordx2 v[100:101], v[38:39], off
	global_load_dwordx2 v[102:103], v[38:39], off offset:512
	global_load_dwordx2 v[104:105], v[38:39], off offset:1024
	global_load_dwordx2 v[106:107], v[38:39], off offset:1536
	s_lshl_b64 s[76:77], s[48:49], 11
	v_lshl_add_u64 v[40:41], v[34:35], 0, s[76:77]
	global_load_dwordx2 v[42:43], v[40:41], off
	global_load_dwordx2 v[60:61], v[40:41], off offset:512
	global_load_dwordx2 v[64:65], v[40:41], off offset:1024
	global_load_dwordx2 v[68:69], v[40:41], off offset:1536
	s_waitcnt vmcnt(7)
	v_lshlrev_b32_e32 v54, 16, v100
	v_and_b32_e32 v55, 0xffff0000, v100
	v_lshlrev_b32_e32 v58, 16, v101
	v_and_b32_e32 v59, 0xffff0000, v101
	s_waitcnt vmcnt(6)
	v_lshlrev_b32_e32 v52, 16, v102
	v_and_b32_e32 v53, 0xffff0000, v102
	v_lshlrev_b32_e32 v62, 16, v103
	v_and_b32_e32 v63, 0xffff0000, v103
	s_waitcnt vmcnt(5)
	v_lshlrev_b32_e32 v50, 16, v104
	v_and_b32_e32 v51, 0xffff0000, v104
	v_lshlrev_b32_e32 v66, 16, v105
	v_and_b32_e32 v67, 0xffff0000, v105
	s_waitcnt vmcnt(4)
	v_lshlrev_b32_e32 v48, 16, v106
	v_and_b32_e32 v49, 0xffff0000, v106
	v_lshlrev_b32_e32 v70, 16, v107
	v_and_b32_e32 v71, 0xffff0000, v107
	s_waitcnt vmcnt(3)
	v_lshlrev_b32_e32 v46, 16, v42
	v_and_b32_e32 v47, 0xffff0000, v42
	v_lshlrev_b32_e32 v56, 16, v43
	v_and_b32_e32 v57, 0xffff0000, v43
	s_waitcnt vmcnt(2)
	v_lshlrev_b32_e32 v44, 16, v60
	v_and_b32_e32 v45, 0xffff0000, v60
	v_lshlrev_b32_e32 v60, 16, v61
	v_and_b32_e32 v61, 0xffff0000, v61
	s_waitcnt vmcnt(1)
	v_lshlrev_b32_e32 v42, 16, v64
	v_and_b32_e32 v43, 0xffff0000, v64
	v_lshlrev_b32_e32 v64, 16, v65
	v_and_b32_e32 v65, 0xffff0000, v65
	s_waitcnt vmcnt(0)
	v_lshlrev_b32_e32 v40, 16, v68
	v_and_b32_e32 v41, 0xffff0000, v68
	v_lshlrev_b32_e32 v68, 16, v69
	v_and_b32_e32 v69, 0xffff0000, v69
